# P4 (SSM output GEMM) epilogue: the 16 u loads and 2 D-gain loads issued together up front, rounds read them from registers, per-round vmcnt waits removed
# speedup vs baseline: 1.0059x; 1.0059x over previous
.LBB0_659:
	v_lshlrev_b32_e32 v66, 6, v100
	v_lshlrev_b32_e32 v67, 2, v1
	v_or_b32_e32 v72, v67, v66
	v_lshlrev_b32_e32 v68, 6, v99
	v_add_u32_e32 v66, s2, v66
	v_lshl_or_b32 v73, v98, 12, v68
	v_ashrrev_i32_e32 v74, 4, v66
	v_add_u32_e32 v80, v74, v73
	v_ashrrev_i32_e32 v81, 31, v80
	s_lshl_b32 s9, s8, 4
	v_or_b32_e32 v75, s9, v67
	v_lshlrev_b64 v[66:67], 5, v[80:81]
	v_lshl_add_u64 v[68:69], s[66:67], 0, v[66:67]
	v_lshlrev_b32_e32 v66, 3, v1
	v_mov_b32_e32 v67, v0
	v_lshl_add_u64 v[68:69], v[68:69], 0, v[66:67]
	v_add_co_u32_e32 v180, vcc, 0x10000, v68
	s_nop 1
	v_addc_co_u32_e32 v181, vcc, 0, v69, vcc
	global_load_dwordx2 v[140:141], v[68:69], off
	global_load_dwordx2 v[142:143], v[68:69], off offset:16
	global_load_dwordx2 v[144:145], v[68:69], off offset:32
	global_load_dwordx2 v[146:147], v[68:69], off offset:48
	global_load_dwordx2 v[148:149], v[180:181], off
	global_load_dwordx2 v[150:151], v[180:181], off offset:16
	global_load_dwordx2 v[152:153], v[180:181], off offset:32
	global_load_dwordx2 v[154:155], v[180:181], off offset:48
	global_load_dwordx2 v[156:157], v[68:69], off offset:64
	global_load_dwordx2 v[158:159], v[68:69], off offset:80
	global_load_dwordx2 v[160:161], v[68:69], off offset:96
	global_load_dwordx2 v[162:163], v[68:69], off offset:112
	global_load_dwordx2 v[164:165], v[180:181], off offset:64
	global_load_dwordx2 v[166:167], v[180:181], off offset:80
	global_load_dwordx2 v[168:169], v[180:181], off offset:96
	global_load_dwordx2 v[170:171], v[180:181], off offset:112
	v_lshlrev_b32_e32 v1, 2, v75
	global_load_dwordx4 v[172:175], v1, s[4:5]
	global_load_dwordx4 v[176:179], v1, s[4:5] offset:32
	s_waitcnt vmcnt(0)
	s_lshl_b32 s0, s13, 24
	s_add_u32 s0, s96, s0
	s_addc_u32 s1, s97, 0
	s_add_i32 s87, s87, s34
	s_add_i32 s62, s62, s40
	s_cmpk_gt_i32 s87, 0x1ff
	v_lshlrev_b32_e32 v82, 16, v140
	v_and_b32_e32 v83, 0xffff0000, v140
	v_pk_fma_f32 v[50:51], v[172:173], v[82:83], v[50:51]
	v_lshlrev_b32_e32 v84, 16, v141
	v_and_b32_e32 v85, 0xffff0000, v141
	v_mul_f32_e32 v70, 0x3d372713, v50
	v_mul_f32_e32 v71, 0x3d372713, v51
	v_mul_f32_e32 v70, v50, v70
	v_mul_f32_e32 v71, v51, v71
	v_fma_f32 v70, v50, v70, v50
	v_fma_f32 v71, v51, v71, v51
	v_mul_f32_e32 v70, 0xbfcc422a, v70
	v_mul_f32_e32 v71, 0xbfcc422a, v71
	v_mul_f32_e32 v70, 0x3fb8aa3b, v70
	v_mul_f32_e32 v71, 0x3fb8aa3b, v71
	v_exp_f32_e32 v70, v70
	v_exp_f32_e32 v71, v71
	v_add_f32_e32 v70, 1.0, v70
	v_add_f32_e32 v71, 1.0, v71
	v_rcp_f32_e32 v70, v70
	v_rcp_f32_e32 v71, v71
	s_nop 0
	v_pk_mul_f32 v[50:51], v[50:51], v[70:71]
	s_nop 0
	v_cvt_pk_bf16_f32 v70, v50, v51
	v_pk_fma_f32 v[50:51], v[174:175], v[84:85], v[52:53]
	s_nop 0
	v_mul_f32_e32 v52, 0x3d372713, v50
	v_mul_f32_e32 v53, 0x3d372713, v51
	v_mul_f32_e32 v52, v50, v52
	v_mul_f32_e32 v53, v51, v53
	v_fma_f32 v52, v50, v52, v50
	v_fma_f32 v53, v51, v53, v51
	v_mul_f32_e32 v52, 0xbfcc422a, v52
	v_mul_f32_e32 v53, 0xbfcc422a, v53
	v_mul_f32_e32 v52, 0x3fb8aa3b, v52
	v_mul_f32_e32 v53, 0x3fb8aa3b, v53
	v_exp_f32_e32 v52, v52
	v_exp_f32_e32 v53, v53
	v_add_f32_e32 v52, 1.0, v52
	v_add_f32_e32 v53, 1.0, v53
	v_rcp_f32_e32 v52, v52
	v_rcp_f32_e32 v53, v53
	s_nop 0
	v_pk_mul_f32 v[50:51], v[50:51], v[52:53]
	s_nop 0
	v_cvt_pk_bf16_f32 v71, v50, v51
	v_lshlrev_b64 v[50:51], 11, v[80:81]
	v_lshl_add_u64 v[52:53], s[0:1], 0, v[50:51]
	v_lshlrev_b32_e32 v50, 1, v75
	v_mov_b32_e32 v51, v0
	v_lshl_add_u64 v[52:53], v[52:53], 0, v[50:51]
	global_store_dwordx2 v[52:53], v[70:71], off
	s_nop 0
	v_lshlrev_b32_e32 v78, 16, v142
	v_and_b32_e32 v79, 0xffff0000, v142
	v_pk_fma_f32 v[54:55], v[176:177], v[78:79], v[54:55]
	v_lshlrev_b32_e32 v76, 16, v143
	v_mul_f32_e32 v68, 0x3d372713, v54
	v_mul_f32_e32 v69, 0x3d372713, v55
	v_mul_f32_e32 v68, v54, v68
	v_mul_f32_e32 v69, v55, v69
	v_fma_f32 v68, v54, v68, v54
	v_fma_f32 v69, v55, v69, v55
	v_mul_f32_e32 v68, 0xbfcc422a, v68
	v_mul_f32_e32 v69, 0xbfcc422a, v69
	v_mul_f32_e32 v68, 0x3fb8aa3b, v68
	v_mul_f32_e32 v69, 0x3fb8aa3b, v69
	v_exp_f32_e32 v68, v68
	v_exp_f32_e32 v69, v69
	v_and_b32_e32 v77, 0xffff0000, v143
	v_pk_fma_f32 v[56:57], v[178:179], v[76:77], v[56:57]
	v_add_f32_e32 v68, 1.0, v68
	v_add_f32_e32 v69, 1.0, v69
	v_rcp_f32_e32 v68, v68
	v_rcp_f32_e32 v69, v69
	s_nop 0
	v_pk_mul_f32 v[54:55], v[54:55], v[68:69]
	s_nop 0
	v_cvt_pk_bf16_f32 v54, v54, v55
	v_mul_f32_e32 v55, 0x3d372713, v56
	v_mul_f32_e32 v55, v56, v55
	v_fma_f32 v55, v56, v55, v56
	v_mul_f32_e32 v55, 0xbfcc422a, v55
	v_mul_f32_e32 v55, 0x3fb8aa3b, v55
	v_exp_f32_e32 v55, v55
	s_nop 0
	v_add_f32_e32 v55, 1.0, v55
	v_rcp_f32_e32 v68, v55
	v_mul_f32_e32 v55, 0x3d372713, v57
	v_mul_f32_e32 v55, v57, v55
	v_fma_f32 v55, v57, v55, v57
	v_mul_f32_e32 v55, 0xbfcc422a, v55
	v_mul_f32_e32 v55, 0x3fb8aa3b, v55
	v_exp_f32_e32 v55, v55
	s_nop 0
	v_add_f32_e32 v55, 1.0, v55
	v_rcp_f32_e32 v69, v55
	s_nop 0
	v_pk_mul_f32 v[56:57], v[56:57], v[68:69]
	s_nop 0
	v_cvt_pk_bf16_f32 v55, v56, v57
	v_add_u32_e32 v68, s2, v72
	global_store_dwordx2 v[52:53], v[54:55], off offset:16
	v_add_u32_e32 v52, 16, v68
	v_ashrrev_i32_e32 v69, 4, v52
	v_add_u32_e32 v56, v69, v73
	v_ashrrev_i32_e32 v57, 31, v56
	v_lshlrev_b64 v[52:53], 5, v[56:57]
	v_lshl_add_u64 v[52:53], s[66:67], 0, v[52:53]
	v_lshl_add_u64 v[52:53], v[52:53], 0, v[66:67]
	s_nop 0
	v_lshlrev_b32_e32 v76, 16, v144
	v_and_b32_e32 v77, 0xffff0000, v144
	v_pk_fma_f32 v[52:53], v[172:173], v[76:77], v[58:59]
	v_lshlrev_b32_e32 v70, 16, v145
	v_mul_f32_e32 v58, 0x3d372713, v52
	v_mul_f32_e32 v59, 0x3d372713, v53
	v_mul_f32_e32 v58, v52, v58
	v_mul_f32_e32 v59, v53, v59
	v_fma_f32 v58, v52, v58, v52
	v_fma_f32 v59, v53, v59, v53
	v_mul_f32_e32 v58, 0xbfcc422a, v58
	v_mul_f32_e32 v59, 0xbfcc422a, v59
	v_mul_f32_e32 v58, 0x3fb8aa3b, v58
	v_mul_f32_e32 v59, 0x3fb8aa3b, v59
	v_exp_f32_e32 v58, v58
	v_exp_f32_e32 v59, v59
	v_and_b32_e32 v71, 0xffff0000, v145
	v_pk_fma_f32 v[54:55], v[174:175], v[70:71], v[60:61]
	v_add_f32_e32 v58, 1.0, v58
	v_add_f32_e32 v59, 1.0, v59
	v_rcp_f32_e32 v58, v58
	v_rcp_f32_e32 v59, v59
	s_nop 0
	v_pk_mul_f32 v[52:53], v[52:53], v[58:59]
	s_nop 0
	v_cvt_pk_bf16_f32 v52, v52, v53
	v_mul_f32_e32 v53, 0x3d372713, v54
	v_mul_f32_e32 v53, v54, v53
	v_fma_f32 v53, v54, v53, v54
	v_mul_f32_e32 v53, 0xbfcc422a, v53
	v_mul_f32_e32 v53, 0x3fb8aa3b, v53
	v_exp_f32_e32 v53, v53
	s_nop 0
	v_add_f32_e32 v53, 1.0, v53
	v_rcp_f32_e32 v58, v53
	v_mul_f32_e32 v53, 0x3d372713, v55
	v_mul_f32_e32 v53, v55, v53
	v_fma_f32 v53, v55, v53, v55
	v_mul_f32_e32 v53, 0xbfcc422a, v53
	v_mul_f32_e32 v53, 0x3fb8aa3b, v53
	v_exp_f32_e32 v53, v53
	s_nop 0
	v_add_f32_e32 v53, 1.0, v53
	v_rcp_f32_e32 v59, v53
	s_nop 0
	v_pk_mul_f32 v[54:55], v[54:55], v[58:59]
	s_nop 0
	v_cvt_pk_bf16_f32 v53, v54, v55
	v_lshlrev_b64 v[54:55], 11, v[56:57]
	v_lshl_add_u64 v[54:55], s[0:1], 0, v[54:55]
	v_lshl_add_u64 v[54:55], v[54:55], 0, v[50:51]
	global_store_dwordx2 v[54:55], v[52:53], off
	v_or_b32_e32 v52, 24, v72
	v_add_u32_e32 v52, s2, v52
	v_ashrrev_i32_e32 v61, 4, v52
	v_add_u32_e32 v54, v61, v73
	v_ashrrev_i32_e32 v55, 31, v54
	v_bitop3_b32 v58, v72, 12, 24 bitop3:0xc8
	v_lshlrev_b64 v[52:53], 5, v[54:55]
	v_lshl_add_u64 v[56:57], s[66:67], 0, v[52:53]
	v_lshlrev_b32_e32 v52, 1, v58
	v_mov_b32_e32 v53, v0
	v_or_b32_e32 v60, s9, v58
	v_lshl_add_u64 v[56:57], v[56:57], 0, v[52:53]
	v_lshlrev_b32_e32 v70, 2, v60
	v_lshlrev_b64 v[54:55], 11, v[54:55]
	v_lshlrev_b32_e32 v78, 16, v146
	v_and_b32_e32 v79, 0xffff0000, v146
	v_pk_fma_f32 v[56:57], v[176:177], v[78:79], v[62:63]
	v_lshlrev_b32_e32 v76, 16, v147
	v_mul_f32_e32 v62, 0x3d372713, v56
	v_mul_f32_e32 v63, 0x3d372713, v57
	v_mul_f32_e32 v62, v56, v62
	v_mul_f32_e32 v63, v57, v63
	v_fma_f32 v62, v56, v62, v56
	v_fma_f32 v63, v57, v63, v57
	v_mul_f32_e32 v62, 0xbfcc422a, v62
	v_mul_f32_e32 v63, 0xbfcc422a, v63
	v_mul_f32_e32 v62, 0x3fb8aa3b, v62
	v_mul_f32_e32 v63, 0x3fb8aa3b, v63
	v_exp_f32_e32 v62, v62
	v_exp_f32_e32 v63, v63
	v_and_b32_e32 v77, 0xffff0000, v147
	v_pk_fma_f32 v[58:59], v[178:179], v[76:77], v[64:65]
	v_add_f32_e32 v62, 1.0, v62
	v_add_f32_e32 v63, 1.0, v63
	v_rcp_f32_e32 v62, v62
	v_rcp_f32_e32 v63, v63
	s_nop 0
	v_pk_mul_f32 v[56:57], v[56:57], v[62:63]
	s_nop 0
	v_cvt_pk_bf16_f32 v56, v56, v57
	v_mul_f32_e32 v57, 0x3d372713, v58
	v_mul_f32_e32 v57, v58, v57
	v_fma_f32 v57, v58, v57, v58
	v_mul_f32_e32 v57, 0xbfcc422a, v57
	v_mul_f32_e32 v57, 0x3fb8aa3b, v57
	v_exp_f32_e32 v57, v57
	s_nop 0
	v_add_f32_e32 v57, 1.0, v57
	v_rcp_f32_e32 v62, v57
	v_mul_f32_e32 v57, 0x3d372713, v59
	v_mul_f32_e32 v57, v59, v57
	v_fma_f32 v57, v59, v57, v59
	v_mul_f32_e32 v57, 0xbfcc422a, v57
	v_mul_f32_e32 v57, 0x3fb8aa3b, v57
	v_exp_f32_e32 v57, v57
	s_nop 0
	v_add_f32_e32 v57, 1.0, v57
	v_rcp_f32_e32 v63, v57
	s_nop 0
	v_pk_mul_f32 v[58:59], v[58:59], v[62:63]
	s_nop 0
	v_cvt_pk_bf16_f32 v57, v58, v59
	v_lshl_add_u64 v[58:59], s[0:1], 0, v[54:55]
	v_lshlrev_b32_e32 v54, 1, v60
	v_mov_b32_e32 v55, v0
	v_lshl_add_u64 v[58:59], v[58:59], 0, v[54:55]
	v_or_b32_e32 v60, 0x800, v73
	global_store_dwordx2 v[58:59], v[56:57], off
	v_add_u32_e32 v58, v74, v60
	v_ashrrev_i32_e32 v59, 31, v58
	v_lshlrev_b64 v[56:57], 5, v[58:59]
	v_lshl_add_u64 v[56:57], s[66:67], 0, v[56:57]
	v_lshl_add_u64 v[56:57], v[56:57], 0, v[66:67]
	v_lshlrev_b32_e32 v76, 16, v148
	v_and_b32_e32 v77, 0xffff0000, v148
	v_pk_fma_f32 v[34:35], v[172:173], v[76:77], v[34:35]
	v_lshlrev_b32_e32 v74, 16, v149
	v_mul_f32_e32 v62, 0x3d372713, v34
	v_mul_f32_e32 v63, 0x3d372713, v35
	v_mul_f32_e32 v62, v34, v62
	v_mul_f32_e32 v63, v35, v63
	v_fma_f32 v62, v34, v62, v34
	v_fma_f32 v63, v35, v63, v35
	v_mul_f32_e32 v62, 0xbfcc422a, v62
	v_mul_f32_e32 v63, 0xbfcc422a, v63
	v_mul_f32_e32 v62, 0x3fb8aa3b, v62
	v_mul_f32_e32 v63, 0x3fb8aa3b, v63
	v_exp_f32_e32 v62, v62
	v_exp_f32_e32 v63, v63
	v_and_b32_e32 v75, 0xffff0000, v149
	v_pk_fma_f32 v[36:37], v[174:175], v[74:75], v[36:37]
	v_add_f32_e32 v62, 1.0, v62
	v_add_f32_e32 v63, 1.0, v63
	v_rcp_f32_e32 v62, v62
	v_rcp_f32_e32 v63, v63
	s_nop 0
	v_pk_mul_f32 v[34:35], v[34:35], v[62:63]
	s_nop 0
	v_cvt_pk_bf16_f32 v34, v34, v35
	v_mul_f32_e32 v35, 0x3d372713, v36
	v_mul_f32_e32 v35, v36, v35
	v_fma_f32 v35, v36, v35, v36
	v_mul_f32_e32 v35, 0xbfcc422a, v35
	v_mul_f32_e32 v35, 0x3fb8aa3b, v35
	v_exp_f32_e32 v35, v35
	s_nop 0
	v_add_f32_e32 v35, 1.0, v35
	v_rcp_f32_e32 v62, v35
	v_mul_f32_e32 v35, 0x3d372713, v37
	v_mul_f32_e32 v35, v37, v35
	v_fma_f32 v35, v37, v35, v37
	v_mul_f32_e32 v35, 0xbfcc422a, v35
	v_mul_f32_e32 v35, 0x3fb8aa3b, v35
	v_exp_f32_e32 v35, v35
	s_nop 0
	v_add_f32_e32 v35, 1.0, v35
	v_rcp_f32_e32 v63, v35
	s_nop 0
	v_pk_mul_f32 v[36:37], v[36:37], v[62:63]
	s_nop 0
	v_cvt_pk_bf16_f32 v35, v36, v37
	v_lshlrev_b64 v[36:37], 11, v[58:59]
	v_lshl_add_u64 v[36:37], s[0:1], 0, v[36:37]
	v_lshl_add_u64 v[58:59], v[36:37], 0, v[50:51]
	global_store_dwordx2 v[58:59], v[34:35], off
	s_nop 0
	v_lshlrev_b32_e32 v62, 16, v150
	v_and_b32_e32 v63, 0xffff0000, v150
	v_pk_fma_f32 v[34:35], v[176:177], v[62:63], v[38:39]
	v_lshlrev_b32_e32 v56, 16, v151
	v_mul_f32_e32 v38, 0x3d372713, v34
	v_mul_f32_e32 v39, 0x3d372713, v35
	v_mul_f32_e32 v38, v34, v38
	v_mul_f32_e32 v39, v35, v39
	v_fma_f32 v38, v34, v38, v34
	v_fma_f32 v39, v35, v39, v35
	v_mul_f32_e32 v38, 0xbfcc422a, v38
	v_mul_f32_e32 v39, 0xbfcc422a, v39
	v_mul_f32_e32 v38, 0x3fb8aa3b, v38
	v_mul_f32_e32 v39, 0x3fb8aa3b, v39
	v_exp_f32_e32 v38, v38
	v_exp_f32_e32 v39, v39
	v_and_b32_e32 v57, 0xffff0000, v151
	v_pk_fma_f32 v[36:37], v[178:179], v[56:57], v[40:41]
	v_add_f32_e32 v38, 1.0, v38
	v_add_f32_e32 v39, 1.0, v39
	v_rcp_f32_e32 v38, v38
	v_rcp_f32_e32 v39, v39
	s_nop 0
	v_pk_mul_f32 v[34:35], v[34:35], v[38:39]
	s_nop 0
	v_cvt_pk_bf16_f32 v34, v34, v35
	v_mul_f32_e32 v35, 0x3d372713, v36
	v_mul_f32_e32 v35, v36, v35
	v_fma_f32 v35, v36, v35, v36
	v_mul_f32_e32 v35, 0xbfcc422a, v35
	v_mul_f32_e32 v35, 0x3fb8aa3b, v35
	v_exp_f32_e32 v35, v35
	s_nop 0
	v_add_f32_e32 v35, 1.0, v35
	v_rcp_f32_e32 v38, v35
	v_mul_f32_e32 v35, 0x3d372713, v37
	v_mul_f32_e32 v35, v37, v35
	v_fma_f32 v35, v37, v35, v37
	v_mul_f32_e32 v35, 0xbfcc422a, v35
	v_mul_f32_e32 v35, 0x3fb8aa3b, v35
	v_exp_f32_e32 v35, v35
	s_nop 0
	v_add_f32_e32 v35, 1.0, v35
	v_rcp_f32_e32 v39, v35
	s_nop 0
	v_pk_mul_f32 v[36:37], v[36:37], v[38:39]
	v_add_u32_e32 v38, v69, v60
	v_cvt_pk_bf16_f32 v35, v36, v37
	v_ashrrev_i32_e32 v39, 31, v38
	global_store_dwordx2 v[58:59], v[34:35], off offset:16
	v_lshlrev_b64 v[34:35], 5, v[38:39]
	v_lshl_add_u64 v[34:35], s[66:67], 0, v[34:35]
	v_lshl_add_u64 v[34:35], v[34:35], 0, v[66:67]
	s_nop 0
	v_lshlrev_b32_e32 v56, 16, v152
	v_and_b32_e32 v57, 0xffff0000, v152
	v_pk_fma_f32 v[34:35], v[172:173], v[56:57], v[42:43]
	v_lshlrev_b32_e32 v40, 16, v153
	v_mul_f32_e32 v42, 0x3d372713, v34
	v_mul_f32_e32 v43, 0x3d372713, v35
	v_mul_f32_e32 v42, v34, v42
	v_mul_f32_e32 v43, v35, v43
	v_fma_f32 v42, v34, v42, v34
	v_fma_f32 v43, v35, v43, v35
	v_mul_f32_e32 v42, 0xbfcc422a, v42
	v_mul_f32_e32 v43, 0xbfcc422a, v43
	v_mul_f32_e32 v42, 0x3fb8aa3b, v42
	v_mul_f32_e32 v43, 0x3fb8aa3b, v43
	v_exp_f32_e32 v42, v42
	v_exp_f32_e32 v43, v43
	v_and_b32_e32 v41, 0xffff0000, v153
	v_pk_fma_f32 v[36:37], v[174:175], v[40:41], v[44:45]
	v_add_f32_e32 v42, 1.0, v42
	v_add_f32_e32 v43, 1.0, v43
	v_rcp_f32_e32 v42, v42
	v_rcp_f32_e32 v43, v43
	s_nop 0
	v_pk_mul_f32 v[34:35], v[34:35], v[42:43]
	s_nop 0
	v_cvt_pk_bf16_f32 v34, v34, v35
	v_mul_f32_e32 v35, 0x3d372713, v36
	v_mul_f32_e32 v35, v36, v35
	v_fma_f32 v35, v36, v35, v36
	v_mul_f32_e32 v35, 0xbfcc422a, v35
	v_mul_f32_e32 v35, 0x3fb8aa3b, v35
	v_exp_f32_e32 v35, v35
	s_nop 0
	v_add_f32_e32 v35, 1.0, v35
	v_rcp_f32_e32 v40, v35
	v_mul_f32_e32 v35, 0x3d372713, v37
	v_mul_f32_e32 v35, v37, v35
	v_fma_f32 v35, v37, v35, v37
	v_mul_f32_e32 v35, 0xbfcc422a, v35
	v_mul_f32_e32 v35, 0x3fb8aa3b, v35
	v_exp_f32_e32 v35, v35
	s_nop 0
	v_add_f32_e32 v35, 1.0, v35
	v_rcp_f32_e32 v41, v35
	s_nop 0
	v_pk_mul_f32 v[36:37], v[36:37], v[40:41]
	s_nop 0
	v_cvt_pk_bf16_f32 v35, v36, v37
	v_lshlrev_b64 v[36:37], 11, v[38:39]
	v_lshl_add_u64 v[36:37], s[0:1], 0, v[36:37]
	v_add_u32_e32 v38, v61, v60
	v_lshl_add_u64 v[36:37], v[36:37], 0, v[50:51]
	v_ashrrev_i32_e32 v39, 31, v38
	global_store_dwordx2 v[36:37], v[34:35], off
	v_lshlrev_b64 v[34:35], 5, v[38:39]
	v_lshl_add_u64 v[34:35], s[66:67], 0, v[34:35]
	v_lshl_add_u64 v[34:35], v[34:35], 0, v[52:53]
	s_nop 0
	v_lshlrev_b32_e32 v42, 16, v154
	v_and_b32_e32 v43, 0xffff0000, v154
	v_pk_fma_f32 v[34:35], v[176:177], v[42:43], v[46:47]
	v_lshlrev_b32_e32 v40, 16, v155
	v_mul_f32_e32 v42, 0x3d372713, v34
	v_mul_f32_e32 v43, 0x3d372713, v35
	v_mul_f32_e32 v42, v34, v42
	v_mul_f32_e32 v43, v35, v43
	v_fma_f32 v42, v34, v42, v34
	v_fma_f32 v43, v35, v43, v35
	v_mul_f32_e32 v42, 0xbfcc422a, v42
	v_mul_f32_e32 v43, 0xbfcc422a, v43
	v_mul_f32_e32 v42, 0x3fb8aa3b, v42
	v_mul_f32_e32 v43, 0x3fb8aa3b, v43
	v_exp_f32_e32 v42, v42
	v_exp_f32_e32 v43, v43
	v_and_b32_e32 v41, 0xffff0000, v155
	v_pk_fma_f32 v[36:37], v[178:179], v[40:41], v[48:49]
	v_add_f32_e32 v42, 1.0, v42
	v_add_f32_e32 v43, 1.0, v43
	v_rcp_f32_e32 v42, v42
	v_rcp_f32_e32 v43, v43
	s_nop 0
	v_pk_mul_f32 v[34:35], v[34:35], v[42:43]
	s_nop 0
	v_cvt_pk_bf16_f32 v34, v34, v35
	v_mul_f32_e32 v35, 0x3d372713, v36
	v_mul_f32_e32 v35, v36, v35
	v_fma_f32 v35, v36, v35, v36
	v_mul_f32_e32 v35, 0xbfcc422a, v35
	v_mul_f32_e32 v35, 0x3fb8aa3b, v35
	v_exp_f32_e32 v35, v35
	s_nop 0
	v_add_f32_e32 v35, 1.0, v35
	v_rcp_f32_e32 v40, v35
	v_mul_f32_e32 v35, 0x3d372713, v37
	v_mul_f32_e32 v35, v37, v35
	v_fma_f32 v35, v37, v35, v37
	v_mul_f32_e32 v35, 0xbfcc422a, v35
	v_mul_f32_e32 v35, 0x3fb8aa3b, v35
	v_exp_f32_e32 v35, v35
	s_nop 0
	v_add_f32_e32 v35, 1.0, v35
	v_rcp_f32_e32 v41, v35
	s_nop 0
	v_pk_mul_f32 v[36:37], v[36:37], v[40:41]
	s_nop 0
	v_cvt_pk_bf16_f32 v35, v36, v37
	v_lshlrev_b64 v[36:37], 11, v[38:39]
	v_lshl_add_u64 v[36:37], s[0:1], 0, v[36:37]
	v_lshl_add_u64 v[36:37], v[36:37], 0, v[54:55]
	global_store_dwordx2 v[36:37], v[34:35], off
	v_add_u32_e32 v34, 32, v68
	v_ashrrev_i32_e32 v37, 4, v34
	v_add_u32_e32 v34, v37, v73
	v_ashrrev_i32_e32 v35, 31, v34
	v_lshlrev_b64 v[38:39], 5, v[34:35]
	v_lshl_add_u64 v[38:39], s[66:67], 0, v[38:39]
	v_lshl_add_u64 v[38:39], v[38:39], 0, v[66:67]
	s_nop 0
	v_lshlrev_b32_e32 v44, 16, v156
	v_and_b32_e32 v45, 0xffff0000, v156
	v_pk_fma_f32 v[18:19], v[172:173], v[44:45], v[18:19]
	v_lshlrev_b32_e32 v42, 16, v157
	v_mul_f32_e32 v36, 0x3d372713, v18
	v_mul_f32_e32 v36, v18, v36
	v_fma_f32 v36, v18, v36, v18
	v_mul_f32_e32 v36, 0xbfcc422a, v36
	v_mul_f32_e32 v36, 0x3fb8aa3b, v36
	v_exp_f32_e32 v36, v36
	v_and_b32_e32 v43, 0xffff0000, v157
	v_pk_fma_f32 v[20:21], v[174:175], v[42:43], v[20:21]
	v_add_f32_e32 v36, 1.0, v36
	v_rcp_f32_e32 v38, v36
	v_mul_f32_e32 v36, 0x3d372713, v19
	v_mul_f32_e32 v36, v19, v36
	v_fma_f32 v36, v19, v36, v19
	v_mul_f32_e32 v36, 0xbfcc422a, v36
	v_mul_f32_e32 v36, 0x3fb8aa3b, v36
	v_exp_f32_e32 v36, v36
	s_nop 0
	v_add_f32_e32 v36, 1.0, v36
	v_rcp_f32_e32 v39, v36
	s_nop 0
	v_pk_mul_f32 v[18:19], v[18:19], v[38:39]
	s_nop 0
	v_cvt_pk_bf16_f32 v18, v18, v19
	v_mul_f32_e32 v19, 0x3d372713, v20
	v_mul_f32_e32 v19, v20, v19
	v_fma_f32 v19, v20, v19, v20
	v_mul_f32_e32 v19, 0xbfcc422a, v19
	v_mul_f32_e32 v19, 0x3fb8aa3b, v19
	v_exp_f32_e32 v19, v19
	s_nop 0
	v_add_f32_e32 v19, 1.0, v19
	v_rcp_f32_e32 v38, v19
	v_mul_f32_e32 v19, 0x3d372713, v21
	v_mul_f32_e32 v19, v21, v19
	v_fma_f32 v19, v21, v19, v21
	v_mul_f32_e32 v19, 0xbfcc422a, v19
	v_mul_f32_e32 v19, 0x3fb8aa3b, v19
	v_exp_f32_e32 v19, v19
	s_nop 0
	v_add_f32_e32 v19, 1.0, v19
	v_rcp_f32_e32 v39, v19
	s_nop 0
	v_pk_mul_f32 v[20:21], v[20:21], v[38:39]
	s_nop 0
	v_cvt_pk_bf16_f32 v19, v20, v21
	v_lshlrev_b64 v[20:21], 11, v[34:35]
	v_lshl_add_u64 v[20:21], s[0:1], 0, v[20:21]
	v_lshl_add_u64 v[20:21], v[20:21], 0, v[50:51]
	global_store_dwordx2 v[20:21], v[18:19], off
	v_or_b32_e32 v18, 40, v72
	v_add_u32_e32 v18, s2, v18
	v_ashrrev_i32_e32 v36, 4, v18
	v_add_u32_e32 v20, v36, v73
	v_ashrrev_i32_e32 v21, 31, v20
	v_bitop3_b32 v38, v72, 12, 40 bitop3:0xc8
	v_lshlrev_b64 v[18:19], 5, v[20:21]
	v_lshl_add_u64 v[34:35], s[66:67], 0, v[18:19]
	v_lshlrev_b32_e32 v18, 1, v38
	v_mov_b32_e32 v19, v0
	v_or_b32_e32 v46, s9, v38
	v_lshl_add_u64 v[34:35], v[34:35], 0, v[18:19]
	v_lshlrev_b32_e32 v34, 2, v46
	v_lshlrev_b64 v[20:21], 11, v[20:21]
	v_lshl_add_u64 v[20:21], s[0:1], 0, v[20:21]
	v_lshlrev_b32_e32 v44, 16, v158
	v_and_b32_e32 v45, 0xffff0000, v158
	v_pk_fma_f32 v[22:23], v[176:177], v[44:45], v[22:23]
	v_lshlrev_b32_e32 v42, 16, v159
	v_mul_f32_e32 v35, 0x3d372713, v22
	v_mul_f32_e32 v35, v22, v35
	v_fma_f32 v35, v22, v35, v22
	v_mul_f32_e32 v35, 0xbfcc422a, v35
	v_mul_f32_e32 v35, 0x3fb8aa3b, v35
	v_exp_f32_e32 v35, v35
	v_and_b32_e32 v43, 0xffff0000, v159
	v_add_f32_e32 v35, 1.0, v35
	v_rcp_f32_e32 v38, v35
	v_mul_f32_e32 v35, 0x3d372713, v23
	v_mul_f32_e32 v35, v23, v35
	v_fma_f32 v35, v23, v35, v23
	v_mul_f32_e32 v35, 0xbfcc422a, v35
	v_mul_f32_e32 v35, 0x3fb8aa3b, v35
	v_exp_f32_e32 v35, v35
	s_nop 0
	v_add_f32_e32 v35, 1.0, v35
	v_rcp_f32_e32 v39, v35
	s_nop 0
	v_pk_mul_f32 v[22:23], v[22:23], v[38:39]
	s_nop 0
	v_cvt_pk_bf16_f32 v38, v22, v23
	v_pk_fma_f32 v[22:23], v[178:179], v[42:43], v[24:25]
	s_nop 0
	v_mul_f32_e32 v24, 0x3d372713, v22
	v_mul_f32_e32 v25, 0x3d372713, v23
	v_mul_f32_e32 v24, v22, v24
	v_mul_f32_e32 v25, v23, v25
	v_fma_f32 v24, v22, v24, v22
	v_fma_f32 v25, v23, v25, v23
	v_mul_f32_e32 v24, 0xbfcc422a, v24
	v_mul_f32_e32 v25, 0xbfcc422a, v25
	v_mul_f32_e32 v24, 0x3fb8aa3b, v24
	v_mul_f32_e32 v25, 0x3fb8aa3b, v25
	v_exp_f32_e32 v24, v24
	v_exp_f32_e32 v25, v25
	v_add_f32_e32 v24, 1.0, v24
	v_add_f32_e32 v25, 1.0, v25
	v_rcp_f32_e32 v24, v24
	v_rcp_f32_e32 v25, v25
	s_nop 0
	v_pk_mul_f32 v[22:23], v[22:23], v[24:25]
	s_nop 0
	v_cvt_pk_bf16_f32 v39, v22, v23
	v_lshlrev_b32_e32 v22, 1, v46
	v_mov_b32_e32 v23, v0
	v_lshl_add_u64 v[20:21], v[20:21], 0, v[22:23]
	global_store_dwordx2 v[20:21], v[38:39], off
	v_add_u32_e32 v20, 48, v68
	v_ashrrev_i32_e32 v35, 4, v20
	v_add_u32_e32 v20, v35, v73
	v_ashrrev_i32_e32 v21, 31, v20
	v_lshlrev_b64 v[24:25], 5, v[20:21]
	v_lshl_add_u64 v[24:25], s[66:67], 0, v[24:25]
	v_lshl_add_u64 v[24:25], v[24:25], 0, v[66:67]
	s_nop 0
	v_lshlrev_b64 v[20:21], 11, v[20:21]
	v_lshl_add_u64 v[20:21], s[0:1], 0, v[20:21]
	v_lshl_add_u64 v[20:21], v[20:21], 0, v[50:51]
	v_lshlrev_b32_e32 v42, 16, v160
	v_and_b32_e32 v43, 0xffff0000, v160
	v_pk_fma_f32 v[26:27], v[172:173], v[42:43], v[26:27]
	v_lshlrev_b32_e32 v24, 16, v161
	v_mul_f32_e32 v38, 0x3d372713, v26
	v_mul_f32_e32 v39, 0x3d372713, v27
	v_mul_f32_e32 v38, v26, v38
	v_mul_f32_e32 v39, v27, v39
	v_fma_f32 v38, v26, v38, v26
	v_fma_f32 v39, v27, v39, v27
	v_mul_f32_e32 v38, 0xbfcc422a, v38
	v_mul_f32_e32 v39, 0xbfcc422a, v39
	v_mul_f32_e32 v38, 0x3fb8aa3b, v38
	v_mul_f32_e32 v39, 0x3fb8aa3b, v39
	v_exp_f32_e32 v38, v38
	v_exp_f32_e32 v39, v39
	v_and_b32_e32 v25, 0xffff0000, v161
	v_pk_fma_f32 v[24:25], v[174:175], v[24:25], v[28:29]
	v_add_f32_e32 v38, 1.0, v38
	v_add_f32_e32 v39, 1.0, v39
	v_rcp_f32_e32 v38, v38
	v_rcp_f32_e32 v39, v39
	s_nop 0
	v_pk_mul_f32 v[26:27], v[26:27], v[38:39]
	s_nop 0
	v_cvt_pk_bf16_f32 v26, v26, v27
	v_mul_f32_e32 v27, 0x3d372713, v24
	v_mul_f32_e32 v27, v24, v27
	v_fma_f32 v27, v24, v27, v24
	v_mul_f32_e32 v27, 0xbfcc422a, v27
	v_mul_f32_e32 v27, 0x3fb8aa3b, v27
	v_exp_f32_e32 v27, v27
	s_nop 0
	v_add_f32_e32 v27, 1.0, v27
	v_rcp_f32_e32 v28, v27
	v_mul_f32_e32 v27, 0x3d372713, v25
	v_mul_f32_e32 v27, v25, v27
	v_fma_f32 v27, v25, v27, v25
	v_mul_f32_e32 v27, 0xbfcc422a, v27
	v_mul_f32_e32 v27, 0x3fb8aa3b, v27
	v_exp_f32_e32 v27, v27
	s_nop 0
	v_add_f32_e32 v27, 1.0, v27
	v_rcp_f32_e32 v29, v27
	s_nop 0
	v_pk_mul_f32 v[24:25], v[24:25], v[28:29]
	s_nop 0
	v_cvt_pk_bf16_f32 v27, v24, v25
	global_store_dwordx2 v[20:21], v[26:27], off
	v_or_b32_e32 v20, 56, v72
	v_add_u32_e32 v20, s2, v20
	v_ashrrev_i32_e32 v28, 4, v20
	v_add_u32_e32 v24, v28, v73
	v_ashrrev_i32_e32 v25, 31, v24
	v_bitop3_b32 v29, v72, 12, 56 bitop3:0xc8
	v_lshlrev_b64 v[20:21], 5, v[24:25]
	v_lshl_add_u64 v[26:27], s[66:67], 0, v[20:21]
	v_lshlrev_b32_e32 v20, 1, v29
	v_mov_b32_e32 v21, v0
	v_or_b32_e32 v46, s9, v29
	v_lshl_add_u64 v[26:27], v[26:27], 0, v[20:21]
	v_lshlrev_b32_e32 v26, 2, v46
	v_lshlrev_b64 v[24:25], 11, v[24:25]
	v_lshlrev_b32_e32 v44, 16, v162
	v_and_b32_e32 v45, 0xffff0000, v162
	v_pk_fma_f32 v[30:31], v[176:177], v[44:45], v[30:31]
	v_lshlrev_b32_e32 v42, 16, v163
	v_mul_f32_e32 v27, 0x3d372713, v30
	v_mul_f32_e32 v27, v30, v27
	v_fma_f32 v27, v30, v27, v30
	v_mul_f32_e32 v27, 0xbfcc422a, v27
	v_mul_f32_e32 v27, 0x3fb8aa3b, v27
	v_exp_f32_e32 v27, v27
	v_and_b32_e32 v43, 0xffff0000, v163
	v_pk_fma_f32 v[32:33], v[178:179], v[42:43], v[32:33]
	v_add_f32_e32 v27, 1.0, v27
	v_rcp_f32_e32 v38, v27
	v_mul_f32_e32 v27, 0x3d372713, v31
	v_mul_f32_e32 v27, v31, v27
	v_fma_f32 v27, v31, v27, v31
	v_mul_f32_e32 v27, 0xbfcc422a, v27
	v_mul_f32_e32 v27, 0x3fb8aa3b, v27
	v_exp_f32_e32 v27, v27
	s_nop 0
	v_add_f32_e32 v27, 1.0, v27
	v_rcp_f32_e32 v39, v27
	v_mul_f32_e32 v27, 0x3d372713, v32
	v_mul_f32_e32 v27, v32, v27
	v_fma_f32 v27, v32, v27, v32
	v_mul_f32_e32 v27, 0xbfcc422a, v27
	v_mul_f32_e32 v27, 0x3fb8aa3b, v27
	v_exp_f32_e32 v27, v27
	v_pk_mul_f32 v[30:31], v[30:31], v[38:39]
	v_add_f32_e32 v27, 1.0, v27
	v_rcp_f32_e32 v38, v27
	v_mul_f32_e32 v27, 0x3d372713, v33
	v_mul_f32_e32 v27, v33, v27
	v_fma_f32 v27, v33, v27, v33
	v_mul_f32_e32 v27, 0xbfcc422a, v27
	v_mul_f32_e32 v27, 0x3fb8aa3b, v27
	v_exp_f32_e32 v27, v27
	v_cvt_pk_bf16_f32 v30, v30, v31
	v_add_f32_e32 v27, 1.0, v27
	v_rcp_f32_e32 v39, v27
	s_nop 0
	v_pk_mul_f32 v[32:33], v[32:33], v[38:39]
	s_nop 0
	v_cvt_pk_bf16_f32 v31, v32, v33
	v_lshl_add_u64 v[32:33], s[0:1], 0, v[24:25]
	v_lshlrev_b32_e32 v24, 1, v46
	v_mov_b32_e32 v25, v0
	v_add_u32_e32 v38, v37, v60
	v_lshl_add_u64 v[32:33], v[32:33], 0, v[24:25]
	v_ashrrev_i32_e32 v39, 31, v38
	global_store_dwordx2 v[32:33], v[30:31], off
	v_lshlrev_b64 v[30:31], 5, v[38:39]
	v_lshl_add_u64 v[30:31], s[66:67], 0, v[30:31]
	v_lshl_add_u64 v[30:31], v[30:31], 0, v[66:67]
	s_nop 0
	v_lshlrev_b32_e32 v42, 16, v164
	v_and_b32_e32 v43, 0xffff0000, v164
	v_pk_fma_f32 v[2:3], v[172:173], v[42:43], v[2:3]
	v_lshlrev_b32_e32 v40, 16, v165
	v_mul_f32_e32 v27, 0x3d372713, v2
	v_mul_f32_e32 v27, v2, v27
	v_fma_f32 v27, v2, v27, v2
	v_mul_f32_e32 v27, 0xbfcc422a, v27
	v_mul_f32_e32 v27, 0x3fb8aa3b, v27
	v_exp_f32_e32 v27, v27
	v_and_b32_e32 v41, 0xffff0000, v165
	v_pk_fma_f32 v[4:5], v[174:175], v[40:41], v[4:5]
	v_add_f32_e32 v27, 1.0, v27
	v_rcp_f32_e32 v30, v27
	v_mul_f32_e32 v27, 0x3d372713, v3
	v_mul_f32_e32 v27, v3, v27
	v_fma_f32 v27, v3, v27, v3
	v_mul_f32_e32 v27, 0xbfcc422a, v27
	v_mul_f32_e32 v27, 0x3fb8aa3b, v27
	v_exp_f32_e32 v27, v27
	s_nop 0
	v_add_f32_e32 v27, 1.0, v27
	v_rcp_f32_e32 v31, v27
	s_nop 0
	v_pk_mul_f32 v[2:3], v[2:3], v[30:31]
	s_nop 0
	v_cvt_pk_bf16_f32 v2, v2, v3
	v_mul_f32_e32 v3, 0x3d372713, v4
	v_mul_f32_e32 v3, v4, v3
	v_fma_f32 v3, v4, v3, v4
	v_mul_f32_e32 v3, 0xbfcc422a, v3
	v_mul_f32_e32 v3, 0x3fb8aa3b, v3
	v_exp_f32_e32 v3, v3
	s_nop 0
	v_add_f32_e32 v3, 1.0, v3
	v_rcp_f32_e32 v30, v3
	v_mul_f32_e32 v3, 0x3d372713, v5
	v_mul_f32_e32 v3, v5, v3
	v_fma_f32 v3, v5, v3, v5
	v_mul_f32_e32 v3, 0xbfcc422a, v3
	v_mul_f32_e32 v3, 0x3fb8aa3b, v3
	v_exp_f32_e32 v3, v3
	s_nop 0
	v_add_f32_e32 v3, 1.0, v3
	v_rcp_f32_e32 v31, v3
	s_nop 0
	v_pk_mul_f32 v[4:5], v[4:5], v[30:31]
	s_nop 0
	v_cvt_pk_bf16_f32 v3, v4, v5
	v_lshlrev_b64 v[4:5], 11, v[38:39]
	v_lshl_add_u64 v[4:5], s[0:1], 0, v[4:5]
	v_add_u32_e32 v30, v36, v60
	v_lshl_add_u64 v[4:5], v[4:5], 0, v[50:51]
	v_ashrrev_i32_e32 v31, 31, v30
	global_store_dwordx2 v[4:5], v[2:3], off
	v_lshlrev_b64 v[2:3], 5, v[30:31]
	v_lshl_add_u64 v[2:3], s[66:67], 0, v[2:3]
	v_lshl_add_u64 v[2:3], v[2:3], 0, v[18:19]
	s_nop 0
	v_lshlrev_b32_e32 v32, 16, v166
	v_and_b32_e32 v33, 0xffff0000, v166
	v_pk_fma_f32 v[2:3], v[176:177], v[32:33], v[6:7]
	v_lshlrev_b32_e32 v18, 16, v167
	v_mul_f32_e32 v6, 0x3d372713, v2
	v_mul_f32_e32 v7, 0x3d372713, v3
	v_mul_f32_e32 v6, v2, v6
	v_mul_f32_e32 v7, v3, v7
	v_fma_f32 v6, v2, v6, v2
	v_fma_f32 v7, v3, v7, v3
	v_mul_f32_e32 v6, 0xbfcc422a, v6
	v_mul_f32_e32 v7, 0xbfcc422a, v7
	v_mul_f32_e32 v6, 0x3fb8aa3b, v6
	v_mul_f32_e32 v7, 0x3fb8aa3b, v7
	v_exp_f32_e32 v6, v6
	v_exp_f32_e32 v7, v7
	v_and_b32_e32 v19, 0xffff0000, v167
	v_pk_fma_f32 v[4:5], v[178:179], v[18:19], v[8:9]
	v_add_f32_e32 v6, 1.0, v6
	v_add_f32_e32 v7, 1.0, v7
	v_rcp_f32_e32 v6, v6
	v_rcp_f32_e32 v7, v7
	s_nop 0
	v_pk_mul_f32 v[2:3], v[2:3], v[6:7]
	s_nop 0
	v_cvt_pk_bf16_f32 v2, v2, v3
	v_mul_f32_e32 v3, 0x3d372713, v4
	v_mul_f32_e32 v3, v4, v3
	v_fma_f32 v3, v4, v3, v4
	v_mul_f32_e32 v3, 0xbfcc422a, v3
	v_mul_f32_e32 v3, 0x3fb8aa3b, v3
	v_exp_f32_e32 v3, v3
	s_nop 0
	v_add_f32_e32 v3, 1.0, v3
	v_rcp_f32_e32 v6, v3
	v_mul_f32_e32 v3, 0x3d372713, v5
	v_mul_f32_e32 v3, v5, v3
	v_fma_f32 v3, v5, v3, v5
	v_mul_f32_e32 v3, 0xbfcc422a, v3
	v_mul_f32_e32 v3, 0x3fb8aa3b, v3
	v_exp_f32_e32 v3, v3
	s_nop 0
	v_add_f32_e32 v3, 1.0, v3
	v_rcp_f32_e32 v7, v3
	s_nop 0
	v_pk_mul_f32 v[4:5], v[4:5], v[6:7]
	s_nop 0
	v_cvt_pk_bf16_f32 v3, v4, v5
	v_lshlrev_b64 v[4:5], 11, v[30:31]
	v_lshl_add_u64 v[4:5], s[0:1], 0, v[4:5]
	v_add_u32_e32 v6, v35, v60
	v_lshl_add_u64 v[4:5], v[4:5], 0, v[22:23]
	v_ashrrev_i32_e32 v7, 31, v6
	global_store_dwordx2 v[4:5], v[2:3], off
	v_lshlrev_b64 v[2:3], 5, v[6:7]
	v_lshl_add_u64 v[2:3], s[66:67], 0, v[2:3]
	v_lshl_add_u64 v[2:3], v[2:3], 0, v[66:67]
	s_nop 0
	v_lshlrev_b32_e32 v18, 16, v168
	v_and_b32_e32 v19, 0xffff0000, v168
	v_pk_fma_f32 v[2:3], v[172:173], v[18:19], v[10:11]
	v_lshlrev_b32_e32 v8, 16, v169
	v_mul_f32_e32 v1, 0x3d372713, v2
	v_mul_f32_e32 v1, v2, v1
	v_fma_f32 v1, v2, v1, v2
	v_mul_f32_e32 v1, 0xbfcc422a, v1
	v_mul_f32_e32 v1, 0x3fb8aa3b, v1
	v_exp_f32_e32 v1, v1
	v_and_b32_e32 v9, 0xffff0000, v169
	v_pk_fma_f32 v[4:5], v[174:175], v[8:9], v[12:13]
	v_add_f32_e32 v1, 1.0, v1
	v_rcp_f32_e32 v10, v1
	v_mul_f32_e32 v1, 0x3d372713, v3
	v_mul_f32_e32 v1, v3, v1
	v_fma_f32 v1, v3, v1, v3
	v_mul_f32_e32 v1, 0xbfcc422a, v1
	v_mul_f32_e32 v1, 0x3fb8aa3b, v1
	v_exp_f32_e32 v1, v1
	s_nop 0
	v_add_f32_e32 v1, 1.0, v1
	v_rcp_f32_e32 v11, v1
	v_mul_f32_e32 v1, 0x3d372713, v4
	v_mul_f32_e32 v1, v4, v1
	v_fma_f32 v1, v4, v1, v4
	v_mul_f32_e32 v1, 0xbfcc422a, v1
	v_mul_f32_e32 v1, 0x3fb8aa3b, v1
	v_exp_f32_e32 v1, v1
	v_pk_mul_f32 v[2:3], v[2:3], v[10:11]
	v_add_f32_e32 v1, 1.0, v1
	v_rcp_f32_e32 v8, v1
	v_mul_f32_e32 v1, 0x3d372713, v5
	v_mul_f32_e32 v1, v5, v1
	v_fma_f32 v1, v5, v1, v5
	v_mul_f32_e32 v1, 0xbfcc422a, v1
	v_mul_f32_e32 v1, 0x3fb8aa3b, v1
	v_exp_f32_e32 v1, v1
	v_cvt_pk_bf16_f32 v2, v2, v3
	v_add_f32_e32 v1, 1.0, v1
	v_rcp_f32_e32 v9, v1
	s_nop 0
	v_pk_mul_f32 v[4:5], v[4:5], v[8:9]
	s_nop 0
	v_cvt_pk_bf16_f32 v3, v4, v5
	v_lshlrev_b64 v[4:5], 11, v[6:7]
	v_lshl_add_u64 v[4:5], s[0:1], 0, v[4:5]
	v_add_u32_e32 v6, v28, v60
	v_lshl_add_u64 v[4:5], v[4:5], 0, v[50:51]
	v_ashrrev_i32_e32 v7, 31, v6
	global_store_dwordx2 v[4:5], v[2:3], off
	v_lshlrev_b64 v[2:3], 5, v[6:7]
	v_lshl_add_u64 v[2:3], s[66:67], 0, v[2:3]
	v_lshl_add_u64 v[2:3], v[2:3], 0, v[20:21]
	s_nop 0
	v_lshlrev_b32_e32 v10, 16, v170
	v_and_b32_e32 v11, 0xffff0000, v170
	v_pk_fma_f32 v[2:3], v[176:177], v[10:11], v[14:15]
	v_lshlrev_b32_e32 v8, 16, v171
	v_mul_f32_e32 v1, 0x3d372713, v2
	v_mul_f32_e32 v1, v2, v1
	v_fma_f32 v1, v2, v1, v2
	v_mul_f32_e32 v1, 0xbfcc422a, v1
	v_mul_f32_e32 v1, 0x3fb8aa3b, v1
	v_exp_f32_e32 v1, v1
	v_and_b32_e32 v9, 0xffff0000, v171
	v_pk_fma_f32 v[4:5], v[178:179], v[8:9], v[16:17]
	v_add_f32_e32 v1, 1.0, v1
	v_rcp_f32_e32 v10, v1
	v_mul_f32_e32 v1, 0x3d372713, v3
	v_mul_f32_e32 v1, v3, v1
	v_fma_f32 v1, v3, v1, v3
	v_mul_f32_e32 v1, 0xbfcc422a, v1
	v_mul_f32_e32 v1, 0x3fb8aa3b, v1
	v_exp_f32_e32 v1, v1
	s_nop 0
	v_add_f32_e32 v1, 1.0, v1
	v_rcp_f32_e32 v11, v1
	v_mul_f32_e32 v1, 0x3d372713, v4
	v_mul_f32_e32 v1, v4, v1
	v_fma_f32 v1, v4, v1, v4
	v_mul_f32_e32 v1, 0xbfcc422a, v1
	v_mul_f32_e32 v1, 0x3fb8aa3b, v1
	v_exp_f32_e32 v1, v1
	v_pk_mul_f32 v[2:3], v[2:3], v[10:11]
	v_add_f32_e32 v1, 1.0, v1
	v_rcp_f32_e32 v8, v1
	v_mul_f32_e32 v1, 0x3d372713, v5
	v_mul_f32_e32 v1, v5, v1
	v_fma_f32 v1, v5, v1, v5
	v_mul_f32_e32 v1, 0xbfcc422a, v1
	v_mul_f32_e32 v1, 0x3fb8aa3b, v1
	v_exp_f32_e32 v1, v1
	v_cvt_pk_bf16_f32 v2, v2, v3
	v_add_f32_e32 v1, 1.0, v1
	v_rcp_f32_e32 v9, v1
	s_nop 0
	v_pk_mul_f32 v[4:5], v[4:5], v[8:9]
	s_nop 0
	v_cvt_pk_bf16_f32 v3, v4, v5
	v_lshlrev_b64 v[4:5], 11, v[6:7]
	v_lshl_add_u64 v[4:5], s[0:1], 0, v[4:5]
	v_lshl_add_u64 v[4:5], v[4:5], 0, v[24:25]
	global_store_dwordx2 v[4:5], v[2:3], off
	s_barrier
	s_cbranch_scc1 .LBB0_743
